# mix GEMM-unit gemm_compute: two-set LDS fragment prefetch (k-step s+1 loads under k-step s MFMAs)
# baseline (speedup 1.0000x reference)
.LBB0_1078:
	s_andn2_b64 vcc, exec, s[76:77]
	s_cbranch_vccnz .LBB0_1080
	s_and_b32 s44, s44, 0x10000
	s_add_i32 s44, s44, 32
	v_add_u32_e32 v224, s44, v166
	v_add_u32_e32 v225, v224, v158
	v_add_u32_e32 v224, v224, v159
	v_add_u32_e32 v226, s44, v165
	v_add_u32_e32 v227, v226, v158
	v_add_u32_e32 v226, v226, v159
	ds_read_b128 v[176:179], v224 offset:32768
	ds_read_b128 v[180:183], v224 offset:36864
	ds_read_b128 v[184:187], v225
	ds_read_b128 v[188:191], v225 offset:4096
	ds_read_b128 v[192:195], v225 offset:8192
	ds_read_b128 v[196:199], v225 offset:12288
	ds_read_b128 v[200:203], v226 offset:32768
	ds_read_b128 v[204:207], v226 offset:36864
	ds_read_b128 v[208:211], v227
	ds_read_b128 v[212:215], v227 offset:4096
	ds_read_b128 v[216:219], v227 offset:8192
	ds_read_b128 v[220:223], v227 offset:12288
	s_waitcnt lgkmcnt(9)
	v_mfma_f32_32x32x16_bf16 v[118:133], v[176:179], v[184:187], v[118:133]
	v_mfma_f32_32x32x16_bf16 v[102:117], v[180:183], v[184:187], v[102:117]
	s_waitcnt lgkmcnt(8)
	v_mfma_f32_32x32x16_bf16 v[86:101], v[176:179], v[188:191], v[86:101]
	v_mfma_f32_32x32x16_bf16 v[70:85], v[180:183], v[188:191], v[70:85]
	s_waitcnt lgkmcnt(7)
	v_mfma_f32_32x32x16_bf16 v[54:69], v[176:179], v[192:195], v[54:69]
	v_mfma_f32_32x32x16_bf16 v[38:53], v[180:183], v[192:195], v[38:53]
	s_waitcnt lgkmcnt(6)
	v_mfma_f32_32x32x16_bf16 v[22:37], v[176:179], v[196:199], v[22:37]
	v_mfma_f32_32x32x16_bf16 v[6:21], v[180:183], v[196:199], v[6:21]
	v_add_u32_e32 v224, s44, v164
	v_add_u32_e32 v225, v224, v158
	v_add_u32_e32 v224, v224, v159
	ds_read_b128 v[176:179], v224 offset:32768
	ds_read_b128 v[180:183], v224 offset:36864
	ds_read_b128 v[184:187], v225
	ds_read_b128 v[188:191], v225 offset:4096
	ds_read_b128 v[192:195], v225 offset:8192
	ds_read_b128 v[196:199], v225 offset:12288
	s_waitcnt lgkmcnt(9)
	v_mfma_f32_32x32x16_bf16 v[118:133], v[200:203], v[208:211], v[118:133]
	v_mfma_f32_32x32x16_bf16 v[102:117], v[204:207], v[208:211], v[102:117]
	s_waitcnt lgkmcnt(8)
	v_mfma_f32_32x32x16_bf16 v[86:101], v[200:203], v[212:215], v[86:101]
	v_mfma_f32_32x32x16_bf16 v[70:85], v[204:207], v[212:215], v[70:85]
	s_waitcnt lgkmcnt(7)
	v_mfma_f32_32x32x16_bf16 v[54:69], v[200:203], v[216:219], v[54:69]
	v_mfma_f32_32x32x16_bf16 v[38:53], v[204:207], v[216:219], v[38:53]
	s_waitcnt lgkmcnt(6)
	v_mfma_f32_32x32x16_bf16 v[22:37], v[200:203], v[220:223], v[22:37]
	v_mfma_f32_32x32x16_bf16 v[6:21], v[204:207], v[220:223], v[6:21]
	v_add_u32_e32 v226, s44, v162
	v_add_u32_e32 v227, v226, v158
	v_add_u32_e32 v226, v226, v159
	ds_read_b128 v[200:203], v226 offset:32768
	ds_read_b128 v[204:207], v226 offset:36864
	ds_read_b128 v[208:211], v227
	ds_read_b128 v[212:215], v227 offset:4096
	ds_read_b128 v[216:219], v227 offset:8192
	ds_read_b128 v[220:223], v227 offset:12288
	s_waitcnt lgkmcnt(9)
	v_mfma_f32_32x32x16_bf16 v[118:133], v[176:179], v[184:187], v[118:133]
	v_mfma_f32_32x32x16_bf16 v[102:117], v[180:183], v[184:187], v[102:117]
	s_waitcnt lgkmcnt(8)
	v_mfma_f32_32x32x16_bf16 v[86:101], v[176:179], v[188:191], v[86:101]
	v_mfma_f32_32x32x16_bf16 v[70:85], v[180:183], v[188:191], v[70:85]
	s_waitcnt lgkmcnt(7)
	v_mfma_f32_32x32x16_bf16 v[54:69], v[176:179], v[192:195], v[54:69]
	v_mfma_f32_32x32x16_bf16 v[38:53], v[180:183], v[192:195], v[38:53]
	s_waitcnt lgkmcnt(6)
	v_mfma_f32_32x32x16_bf16 v[22:37], v[176:179], v[196:199], v[22:37]
	v_mfma_f32_32x32x16_bf16 v[6:21], v[180:183], v[196:199], v[6:21]
	s_waitcnt lgkmcnt(3)
	v_mfma_f32_32x32x16_bf16 v[118:133], v[200:203], v[208:211], v[118:133]
	v_mfma_f32_32x32x16_bf16 v[102:117], v[204:207], v[208:211], v[102:117]
	s_waitcnt lgkmcnt(2)
	v_mfma_f32_32x32x16_bf16 v[86:101], v[200:203], v[212:215], v[86:101]
	v_mfma_f32_32x32x16_bf16 v[70:85], v[204:207], v[212:215], v[70:85]
	s_waitcnt lgkmcnt(1)
	v_mfma_f32_32x32x16_bf16 v[54:69], v[200:203], v[216:219], v[54:69]
	v_mfma_f32_32x32x16_bf16 v[38:53], v[204:207], v[216:219], v[38:53]
	s_waitcnt lgkmcnt(0)
	v_mfma_f32_32x32x16_bf16 v[22:37], v[200:203], v[220:223], v[22:37]
	v_mfma_f32_32x32x16_bf16 v[6:21], v[204:207], v[220:223], v[6:21]

.LBB0_1084:
	s_andn2_b64 vcc, exec, s[72:73]
	s_cbranch_vccnz .LBB0_1086
	v_add_u32_e32 v224, s17, v166
	v_add_u32_e32 v225, v224, v158
	v_add_u32_e32 v224, v224, v159
	v_add_u32_e32 v226, s17, v165
	v_add_u32_e32 v227, v226, v158
	v_add_u32_e32 v226, v226, v159
	ds_read_b128 v[176:179], v224 offset:32768
	ds_read_b128 v[180:183], v224 offset:36864
	ds_read_b128 v[184:187], v225
	ds_read_b128 v[188:191], v225 offset:4096
	ds_read_b128 v[192:195], v225 offset:8192
	ds_read_b128 v[196:199], v225 offset:12288
	ds_read_b128 v[200:203], v226 offset:32768
	ds_read_b128 v[204:207], v226 offset:36864
	ds_read_b128 v[208:211], v227
	ds_read_b128 v[212:215], v227 offset:4096
	ds_read_b128 v[216:219], v227 offset:8192
	ds_read_b128 v[220:223], v227 offset:12288
	s_waitcnt lgkmcnt(9)
	v_mfma_f32_32x32x16_bf16 v[118:133], v[176:179], v[184:187], v[118:133]
	v_mfma_f32_32x32x16_bf16 v[102:117], v[180:183], v[184:187], v[102:117]
	s_waitcnt lgkmcnt(8)
	v_mfma_f32_32x32x16_bf16 v[86:101], v[176:179], v[188:191], v[86:101]
	v_mfma_f32_32x32x16_bf16 v[70:85], v[180:183], v[188:191], v[70:85]
	s_waitcnt lgkmcnt(7)
	v_mfma_f32_32x32x16_bf16 v[54:69], v[176:179], v[192:195], v[54:69]
	v_mfma_f32_32x32x16_bf16 v[38:53], v[180:183], v[192:195], v[38:53]
	s_waitcnt lgkmcnt(6)
	v_mfma_f32_32x32x16_bf16 v[22:37], v[176:179], v[196:199], v[22:37]
	v_mfma_f32_32x32x16_bf16 v[6:21], v[180:183], v[196:199], v[6:21]
	v_add_u32_e32 v224, s17, v164
	v_add_u32_e32 v225, v224, v158
	v_add_u32_e32 v224, v224, v159
	ds_read_b128 v[176:179], v224 offset:32768
	ds_read_b128 v[180:183], v224 offset:36864
	ds_read_b128 v[184:187], v225
	ds_read_b128 v[188:191], v225 offset:4096
	ds_read_b128 v[192:195], v225 offset:8192
	ds_read_b128 v[196:199], v225 offset:12288
	s_waitcnt lgkmcnt(9)
	v_mfma_f32_32x32x16_bf16 v[118:133], v[200:203], v[208:211], v[118:133]
	v_mfma_f32_32x32x16_bf16 v[102:117], v[204:207], v[208:211], v[102:117]
	s_waitcnt lgkmcnt(8)
	v_mfma_f32_32x32x16_bf16 v[86:101], v[200:203], v[212:215], v[86:101]
	v_mfma_f32_32x32x16_bf16 v[70:85], v[204:207], v[212:215], v[70:85]
	s_waitcnt lgkmcnt(7)
	v_mfma_f32_32x32x16_bf16 v[54:69], v[200:203], v[216:219], v[54:69]
	v_mfma_f32_32x32x16_bf16 v[38:53], v[204:207], v[216:219], v[38:53]
	s_waitcnt lgkmcnt(6)
	v_mfma_f32_32x32x16_bf16 v[22:37], v[200:203], v[220:223], v[22:37]
	v_mfma_f32_32x32x16_bf16 v[6:21], v[204:207], v[220:223], v[6:21]
	v_add_u32_e32 v226, s17, v162
	v_add_u32_e32 v227, v226, v158
	v_add_u32_e32 v226, v226, v159
	ds_read_b128 v[200:203], v226 offset:32768
	ds_read_b128 v[204:207], v226 offset:36864
	ds_read_b128 v[208:211], v227
	ds_read_b128 v[212:215], v227 offset:4096
	ds_read_b128 v[216:219], v227 offset:8192
	ds_read_b128 v[220:223], v227 offset:12288
	s_waitcnt lgkmcnt(9)
	v_mfma_f32_32x32x16_bf16 v[118:133], v[176:179], v[184:187], v[118:133]
	v_mfma_f32_32x32x16_bf16 v[102:117], v[180:183], v[184:187], v[102:117]
	s_waitcnt lgkmcnt(8)
	v_mfma_f32_32x32x16_bf16 v[86:101], v[176:179], v[188:191], v[86:101]
	v_mfma_f32_32x32x16_bf16 v[70:85], v[180:183], v[188:191], v[70:85]
	s_waitcnt lgkmcnt(7)
	v_mfma_f32_32x32x16_bf16 v[54:69], v[176:179], v[192:195], v[54:69]
	v_mfma_f32_32x32x16_bf16 v[38:53], v[180:183], v[192:195], v[38:53]
	s_waitcnt lgkmcnt(6)
	v_mfma_f32_32x32x16_bf16 v[22:37], v[176:179], v[196:199], v[22:37]
	v_mfma_f32_32x32x16_bf16 v[6:21], v[180:183], v[196:199], v[6:21]
	s_waitcnt lgkmcnt(3)
	v_mfma_f32_32x32x16_bf16 v[118:133], v[200:203], v[208:211], v[118:133]
	v_mfma_f32_32x32x16_bf16 v[102:117], v[204:207], v[208:211], v[102:117]
	s_waitcnt lgkmcnt(2)
	v_mfma_f32_32x32x16_bf16 v[86:101], v[200:203], v[212:215], v[86:101]
	v_mfma_f32_32x32x16_bf16 v[70:85], v[204:207], v[212:215], v[70:85]
	s_waitcnt lgkmcnt(1)
	v_mfma_f32_32x32x16_bf16 v[54:69], v[200:203], v[216:219], v[54:69]
	v_mfma_f32_32x32x16_bf16 v[38:53], v[204:207], v[216:219], v[38:53]
	s_waitcnt lgkmcnt(0)
	v_mfma_f32_32x32x16_bf16 v[22:37], v[200:203], v[220:223], v[22:37]
	v_mfma_f32_32x32x16_bf16 v[6:21], v[204:207], v[220:223], v[6:21]
